# mix_b radix select: suffix scan of bin totals by DPP row_shl adds and v_readlane instead of six ds_bpermute round trips; hit-lane broadcasts by v_readlane; nop padding keeps later code alignment
# baseline (speedup 1.0000x reference)
; DI float shidx(float v, int src) { return __int_as_float(__builtin_amdgcn_ds_bpermute(src << 2, __float_as_int(v))); }
; DI int shidx(int v, int src) { return __builtin_amdgcn_ds_bpermute(src << 2, v); }
; DI void phase_mix_b(int wv_, int vb_, int nvb_, char* ws_, const Ctx& p, char* smem) {
;     ...
;         unsigned long long mk = __ballot(hit);
;         int src = mk ? (__ffsll((long long)mk) - 1) : 0;
;         bin = shidx(bin, src); nn = shidx(nn, src);
;         prefix = (prefix << 8) | (unsigned)bin; need = nn;
.LBB0_400:
	s_or_b64 exec, exec, s[34:35]
	v_cndmask_b32_e64 v3, 0, 1, s[18:19]
	v_cmp_ne_u32_e32 vcc, 0, v3
	s_ff1_i32_b64 s18, vcc
	s_cmp_lg_u64 vcc, 0
	s_cselect_b32 s18, s18, 0
	s_nop 3
	v_readlane_b32 s4, v2, s18
	v_readlane_b32 s5, v10, s18
	s_mov_b32 s62, 0
	s_mov_b64 s[18:19], 0
	s_and_b64 vcc, exec, s[56:57]
	v_mov_b32_e32 v2, s4
	v_mov_b32_e32 v10, s5
	v_lshl_or_b32 v11, v11, 8, v2
	s_cbranch_vccnz .LBB0_429

; DI int shdown(int v, int d) { const int l = lane_now(); return __builtin_amdgcn_ds_bpermute((l + d < 64 ? l + d : l) << 2, v); }
; DI void phase_mix_b(int wv_, int vb_, int nvb_, char* ws_, const Ctx& p, char* smem) {
;     ...
;         asm volatile("s_waitcnt lgkmcnt(0)" ::: "memory");
;         uint4 hv = *(const uint4*)(myH + lane * 4);
;         int tot = (int)(hv.x + hv.y + hv.z + hv.w);
;         int incl = tot;
; #pragma unroll
;         for (int off = 1; off < 64; off <<= 1) { int v = shdown(incl, off); if (lane + off < 64) incl += v; }
;         int above = incl - tot;
;         bool hit = (above < need) && (need <= incl);
;         int bin = 0, nn = need;
;         if (hit) {
;           int a = above;
;           if (need <= a + (int)hv.w) { bin = 3; nn = need - a; }
;           else { a += hv.w; if (need <= a + (int)hv.z) { bin = 2; nn = need - a; }
;             else { a += hv.z; if (need <= a + (int)hv.y) { bin = 1; nn = need - a; } else { a += hv.y; bin = 0; nn = need - a; } } }
;           bin += lane * 4;
.LBB0_426:
	s_or_b64 exec, exec, s[96:97]
	s_waitcnt lgkmcnt(0)
	ds_read_b128 v[2:5], v15
	s_xor_b64 s[56:57], s[18:19], -1
	s_mov_b64 s[10:11], exec
	v_cmp_gt_u32_e64 s[8:9], 16, v7
	s_waitcnt lgkmcnt(0)
	v_add_u32_e32 v2, v3, v2
	v_add3_u32 v19, v2, v4, v5
	v_mov_b32_e32 v20, v19
	s_nop 1
	v_add_u32_dpp v20, v20, v20 row_shl:1 row_mask:0xf bank_mask:0xf bound_ctrl:1
	s_nop 1
	v_add_u32_dpp v20, v20, v20 row_shl:2 row_mask:0xf bank_mask:0xf bound_ctrl:1
	s_nop 1
	v_add_u32_dpp v20, v20, v20 row_shl:4 row_mask:0xf bank_mask:0xf bound_ctrl:1
	s_nop 1
	v_add_u32_dpp v20, v20, v20 row_shl:8 row_mask:0xf bank_mask:0xf bound_ctrl:1
	s_nop 1
	v_readlane_b32 s4, v20, 16
	v_readlane_b32 s5, v20, 32
	v_readlane_b32 s6, v20, 48
	v_mov_b32_e32 v2, 0
	s_mov_b64 exec, s[12:13]
	v_add_u32_e32 v20, s6, v20
	s_mov_b64 exec, s[14:15]
	v_add_u32_e32 v20, s5, v20
	s_mov_b64 exec, s[8:9]
	v_add_u32_e32 v20, s4, v20
	s_mov_b64 exec, s[10:11]
	v_sub_u32_e32 v18, v20, v19
	v_cmp_lt_i32_e32 vcc, v18, v10
	v_cmp_le_i32_e64 s[18:19], v10, v20
	s_and_b64 s[18:19], s[18:19], vcc
	s_and_saveexec_b64 s[34:35], s[18:19]
	s_cbranch_execz .LBB0_400
	v_add_u32_e32 v2, v18, v5
	v_cmp_gt_i32_e32 vcc, v10, v2
	v_mov_b32_e32 v5, 3
	s_and_saveexec_b64 s[96:97], vcc
	s_cbranch_execz .LBB0_399
	v_add_u32_e32 v4, v2, v4
	v_add_u32_e32 v3, v4, v3
	v_cmp_le_i32_e32 vcc, v10, v3
	s_nop 1
	v_cndmask_b32_e64 v5, 0, 1, vcc
	v_cndmask_b32_e32 v3, v3, v4, vcc
	v_cmp_gt_i32_e32 vcc, v10, v4
	s_nop 1
	v_cndmask_b32_e32 v5, 2, v5, vcc
	v_cndmask_b32_e32 v18, v2, v3, vcc
	s_branch .LBB0_399

; DI void phase_mix_b(int wv_, int vb_, int nvb_, char* ws_, const Ctx& p, char* smem) {
;     ...
;       u16* mySel = sel + wave * 256;
;       int cnt = 0;
;       if (n <= 256) {
;         for (int j = lane; j < 256; j += 64) mySel[j] = (u16)((j < n) ? j : 0);
;         cnt = n;
;       } else {
;         int eqseen = 0;
.LBB0_447:
	s_nop 0
	s_nop 0
	s_nop 0
	s_nop 0
	s_nop 0
	s_nop 0
	s_nop 0
	s_nop 0
	s_nop 0
	s_nop 0
	s_nop 0
	s_nop 0
	s_nop 0
	s_mov_b64 s[2:3], 0
